# out-proj->gate-up seam without grid barrier (per-row-tile XN counters, write-through XN), split-K units moved to workgroups 224..255
# baseline (speedup 1.0000x reference)
;     __device__ bool next(int i, Unit& u) const {
;         const long L = (long)i * G + c; if (c < 0 || L >= tot) return false;
;         if (nsplit > 0 && L >= nwg) { const int r = (int)L - nwg, su = r / nsplit, sp = r % nsplit; u.pm = nMfull + su / nN; u.pn = su % nN; u.z = 0; u.k0 = sp * 256; u.nt = 4; u.split = 1; return true; }
; __global__ void __launch_bounds__(512, 2) hybrid_fwd(Params P) {
;     ...
;             pg8::Gemm g{MIX, WOUT + (size_t)l * D * D, D, D, D, 0, 0}; pg8::Order S; S.init_split(MP / 256, MS / 256, D / 256, G, bid, D / 64);
.LBB0_1422:
	s_add_i32 s60, s60, 1
	s_mul_i32 s0, s60, s59
	s_mul_hi_u32 s1, s60, s42
	s_add_i32 s1, s1, s0
	s_mul_i32 s0, s60, s42
	s_sub_i32 s5, s44, 0xe0
	s_cmp_lt_i32 s5, 0
	s_cselect_b32 s5, 0x1000, s5
	s_add_u32 s0, s0, s5
	s_addc_u32 s1, s1, 0
	v_cmp_gt_i64_e32 vcc, s[0:1], v[172:173]
	v_cmp_lt_i64_e64 s[2:3], s[0:1], v[170:171]
	s_cbranch_vccnz .LBB0_1431
	v_cmp_lt_i64_e32 vcc, s[0:1], v[174:175]
	s_mov_b64 s[30:31], -1
	s_cbranch_vccnz .LBB0_1425
	s_bfe_u32 s5, s0, 0x60002
	s_cmp_gt_u32 s5, 3
	v_sub_co_u32_e64 v0, s[26:27], s5, 4
	s_cselect_b32 s24, 0x41, 64
	s_and_b64 s[26:27], s[26:27], exec
	v_readfirstlane_b32 s25, v0
	s_cselect_b32 s26, s5, s25
	s_lshl_b32 s5, s0, 8
	s_and_b32 s28, s5, 0x300
	s_mov_b64 s[30:31], 0

; __device__ __forceinline__ unsigned cvt_pk_bf16(float lo, float hi) { const f32x2_t v = {lo, hi}; const bf16x2_t b = __builtin_convertvector(v, bf16x2_t); return __builtin_bit_cast(unsigned, b); }
; template <bool FINAL>
; __device__ __forceinline__ void norm_rows(const float* xp, const float* xs, const float* X, const float* g, const float* sh, const float* sc, bf16_t* XN, float* out, int gw, int NGW, int lane, const float* part, int nsplit) {
;     ...
;         for (int j = 0; j < 4; ++j) { const int col = 4 * lane + 256 * j; const f32x4 gg = *(const f32x4*)(g + col);
;             if (FINAL) { *(f32x4*)(out + (size_t)row * D + col) = v[j] * rstd * gg; }
;             else { const f32x4 s1 = *(const f32x4*)(sc + (size_t)mr * 6144 + col), s0 = *(const f32x4*)(sh + (size_t)mr * 6144 + col);
;                 const f32x4 h = v[j] * rstd * gg * (s1 + 1.0f) + s0;
;                 *(u32x2*)(XN + (size_t)row * D + col) = (u32x2){cvt_pk_bf16(h[0], h[1]), cvt_pk_bf16(h[2], h[3])}; } }
.Lfz_out_norstd:
	s_waitcnt lgkmcnt(0)
	s_barrier
	v_lshlrev_b32_e32 v145, 2, v142
	v_add_u32_e32 v145, 0x21800, v145
	ds_read_b32 v188, v145
	ds_read_b32 v189, v145 offset:64
	ds_read_b32 v190, v145 offset:128
	ds_read_b32 v191, v145 offset:192
	ds_read_b32 v192, v145 offset:512
	ds_read_b32 v193, v145 offset:576
	ds_read_b32 v194, v145 offset:640
	ds_read_b32 v195, v145 offset:704
	s_waitcnt vmcnt(0) lgkmcnt(0)
	v_pk_add_f32 v[226:227], v[226:227], 1.0 op_sel_hi:[1,0]
	v_pk_add_f32 v[224:225], v[224:225], 1.0 op_sel_hi:[1,0]
	v_pk_add_f32 v[230:231], v[230:231], 1.0 op_sel_hi:[1,0]
	v_pk_add_f32 v[228:229], v[228:229], 1.0 op_sel_hi:[1,0]
	v_pk_add_f32 v[234:235], v[234:235], 1.0 op_sel_hi:[1,0]
	v_pk_add_f32 v[232:233], v[232:233], 1.0 op_sel_hi:[1,0]
	v_pk_add_f32 v[238:239], v[238:239], 1.0 op_sel_hi:[1,0]
	v_pk_add_f32 v[236:237], v[236:237], 1.0 op_sel_hi:[1,0]
	v_mul_f32_e32 v124, v124, v188
	v_mul_f32_e32 v125, v125, v188
	v_mul_f32_e32 v126, v126, v188
	v_mul_f32_e32 v127, v127, v188
	v_pk_mul_f32 v[124:125], v[208:209], v[124:125]
	v_pk_mul_f32 v[126:127], v[210:211], v[126:127]
	v_pk_fma_f32 v[126:127], v[226:227], v[126:127], v[242:243]
	v_pk_fma_f32 v[124:125], v[224:225], v[124:125], v[240:241]
	s_nop 0
	v_cvt_pk_bf16_f32 v124, v124, v125
	v_cvt_pk_bf16_f32 v125, v126, v127
	global_store_dwordx2 v[128:129], v[124:125], off sc0 sc1
	v_mul_f32_e32 v120, v120, v188
	v_mul_f32_e32 v121, v121, v188
	v_mul_f32_e32 v122, v122, v188
	v_mul_f32_e32 v123, v123, v188
	v_pk_mul_f32 v[120:121], v[212:213], v[120:121]
	v_pk_mul_f32 v[122:123], v[214:215], v[122:123]
	v_pk_fma_f32 v[122:123], v[230:231], v[122:123], v[246:247]
	v_pk_fma_f32 v[120:121], v[228:229], v[120:121], v[244:245]
	s_nop 0
	v_cvt_pk_bf16_f32 v120, v120, v121
	v_cvt_pk_bf16_f32 v121, v122, v123
	global_store_dwordx2 v[128:129], v[120:121], off offset:32 sc0 sc1
	v_mul_f32_e32 v116, v116, v188
	v_mul_f32_e32 v117, v117, v188
	v_mul_f32_e32 v118, v118, v188
	v_mul_f32_e32 v119, v119, v188
	v_pk_mul_f32 v[116:117], v[216:217], v[116:117]
	v_pk_mul_f32 v[118:119], v[218:219], v[118:119]
	v_pk_fma_f32 v[118:119], v[234:235], v[118:119], v[250:251]
	v_pk_fma_f32 v[116:117], v[232:233], v[116:117], v[248:249]
	s_nop 0
	v_cvt_pk_bf16_f32 v116, v116, v117
	v_cvt_pk_bf16_f32 v117, v118, v119
	global_store_dwordx2 v[128:129], v[116:117], off offset:256 sc0 sc1
	v_mul_f32_e32 v112, v112, v188
	v_mul_f32_e32 v113, v113, v188
	v_mul_f32_e32 v114, v114, v188
	v_mul_f32_e32 v115, v115, v188
	v_pk_mul_f32 v[112:113], v[220:221], v[112:113]
	v_pk_mul_f32 v[114:115], v[222:223], v[114:115]
	v_pk_fma_f32 v[114:115], v[238:239], v[114:115], v[186:187]
	v_pk_fma_f32 v[112:113], v[236:237], v[112:113], v[184:185]
	s_nop 0
	v_cvt_pk_bf16_f32 v112, v112, v113
	v_cvt_pk_bf16_f32 v113, v114, v115
	global_store_dwordx2 v[128:129], v[112:113], off offset:288 sc0 sc1
	v_add_co_u32_e32 v128, vcc, 0x8000, v128
	s_nop 1
	v_addc_co_u32_e32 v129, vcc, 0, v129, vcc
	v_mul_f32_e32 v108, v108, v189
	v_mul_f32_e32 v109, v109, v189
	v_mul_f32_e32 v110, v110, v189
	v_mul_f32_e32 v111, v111, v189
	v_pk_mul_f32 v[108:109], v[208:209], v[108:109]
	v_pk_mul_f32 v[110:111], v[210:211], v[110:111]
	v_pk_fma_f32 v[110:111], v[226:227], v[110:111], v[242:243]
	v_pk_fma_f32 v[108:109], v[224:225], v[108:109], v[240:241]
	s_nop 0
	v_cvt_pk_bf16_f32 v108, v108, v109
	v_cvt_pk_bf16_f32 v109, v110, v111
	global_store_dwordx2 v[128:129], v[108:109], off sc0 sc1
	v_mul_f32_e32 v104, v104, v189
	v_mul_f32_e32 v105, v105, v189
	v_mul_f32_e32 v106, v106, v189
	v_mul_f32_e32 v107, v107, v189
	v_pk_mul_f32 v[104:105], v[212:213], v[104:105]
	v_pk_mul_f32 v[106:107], v[214:215], v[106:107]
	v_pk_fma_f32 v[106:107], v[230:231], v[106:107], v[246:247]
	v_pk_fma_f32 v[104:105], v[228:229], v[104:105], v[244:245]
	s_nop 0
	v_cvt_pk_bf16_f32 v104, v104, v105
	v_cvt_pk_bf16_f32 v105, v106, v107
	global_store_dwordx2 v[128:129], v[104:105], off offset:32 sc0 sc1
	v_mul_f32_e32 v100, v100, v189
	v_mul_f32_e32 v101, v101, v189
	v_mul_f32_e32 v102, v102, v189
	v_mul_f32_e32 v103, v103, v189
	v_pk_mul_f32 v[100:101], v[216:217], v[100:101]
	v_pk_mul_f32 v[102:103], v[218:219], v[102:103]
	v_pk_fma_f32 v[102:103], v[234:235], v[102:103], v[250:251]
	v_pk_fma_f32 v[100:101], v[232:233], v[100:101], v[248:249]
	s_nop 0
	v_cvt_pk_bf16_f32 v100, v100, v101
	v_cvt_pk_bf16_f32 v101, v102, v103
	global_store_dwordx2 v[128:129], v[100:101], off offset:256 sc0 sc1
	v_mul_f32_e32 v96, v96, v189
	v_mul_f32_e32 v97, v97, v189
	v_mul_f32_e32 v98, v98, v189
	v_mul_f32_e32 v99, v99, v189
	v_pk_mul_f32 v[96:97], v[220:221], v[96:97]
	v_pk_mul_f32 v[98:99], v[222:223], v[98:99]
	v_pk_fma_f32 v[98:99], v[238:239], v[98:99], v[186:187]
	v_pk_fma_f32 v[96:97], v[236:237], v[96:97], v[184:185]
	s_nop 0
	v_cvt_pk_bf16_f32 v96, v96, v97
	v_cvt_pk_bf16_f32 v97, v98, v99
	global_store_dwordx2 v[128:129], v[96:97], off offset:288 sc0 sc1
	v_add_co_u32_e32 v128, vcc, 0x8000, v128
	s_nop 1
	v_addc_co_u32_e32 v129, vcc, 0, v129, vcc
	v_mul_f32_e32 v92, v92, v190
	v_mul_f32_e32 v93, v93, v190
	v_mul_f32_e32 v94, v94, v190
	v_mul_f32_e32 v95, v95, v190
	v_pk_mul_f32 v[92:93], v[208:209], v[92:93]
	v_pk_mul_f32 v[94:95], v[210:211], v[94:95]
	v_pk_fma_f32 v[94:95], v[226:227], v[94:95], v[242:243]
	v_pk_fma_f32 v[92:93], v[224:225], v[92:93], v[240:241]
	s_nop 0
	v_cvt_pk_bf16_f32 v92, v92, v93
	v_cvt_pk_bf16_f32 v93, v94, v95
	global_store_dwordx2 v[128:129], v[92:93], off sc0 sc1
	v_mul_f32_e32 v88, v88, v190
	v_mul_f32_e32 v89, v89, v190
	v_mul_f32_e32 v90, v90, v190
	v_mul_f32_e32 v91, v91, v190
	v_pk_mul_f32 v[88:89], v[212:213], v[88:89]
	v_pk_mul_f32 v[90:91], v[214:215], v[90:91]
; __device__ __forceinline__ unsigned cvt_pk_bf16(float lo, float hi) { const f32x2_t v = {lo, hi}; const bf16x2_t b = __builtin_convertvector(v, bf16x2_t); return __builtin_bit_cast(unsigned, b); }
;     __device__ __forceinline__ void operator()(const Acc& acc, const Unit& u, int wr, int wc, int fr, int fq) const {
;     ...
;                     for (int n = 0; n < 2; ++n) { const int col = u.pn * 256 + bj * 128 + wc * 32 + n * 16 + fq * 4;
;                         const f32x4 ga = *(const f32x4*)(gp + col) * acc[ai][bj][m][n];
;                         if (u.split) { *(f32x4*)(part + ((size_t)(u.k0 >> 8) * MS + (row - MP)) * D + col) = ga;
;                         } else *(f32x4*)(X + (size_t)row * D + col) = *(const f32x4*)(base + col) + ga; } }
; template <bool FINAL>
; __device__ __forceinline__ void norm_rows(const float* xp, const float* xs, const float* X, const float* g, const float* sh, const float* sc, bf16_t* XN, float* out, int gw, int NGW, int lane, const float* part, int nsplit) {
;     ...
;         for (int j = 0; j < 4; ++j) { const int col = 4 * lane + 256 * j; const f32x4 gg = *(const f32x4*)(g + col);
;             if (FINAL) { *(f32x4*)(out + (size_t)row * D + col) = v[j] * rstd * gg; }
;             else { const f32x4 s1 = *(const f32x4*)(sc + (size_t)mr * 6144 + col), s0 = *(const f32x4*)(sh + (size_t)mr * 6144 + col);
;                 const f32x4 h = v[j] * rstd * gg * (s1 + 1.0f) + s0;
;                 *(u32x2*)(XN + (size_t)row * D + col) = (u32x2){cvt_pk_bf16(h[0], h[1]), cvt_pk_bf16(h[2], h[3])}; } }
	v_pk_fma_f32 v[90:91], v[230:231], v[90:91], v[246:247]
	v_pk_fma_f32 v[88:89], v[228:229], v[88:89], v[244:245]
	s_nop 0
	v_cvt_pk_bf16_f32 v88, v88, v89
	v_cvt_pk_bf16_f32 v89, v90, v91
	global_store_dwordx2 v[128:129], v[88:89], off offset:32 sc0 sc1
	v_mul_f32_e32 v84, v84, v190
	v_mul_f32_e32 v85, v85, v190
	v_mul_f32_e32 v86, v86, v190
	v_mul_f32_e32 v87, v87, v190
	v_pk_mul_f32 v[84:85], v[216:217], v[84:85]
	v_pk_mul_f32 v[86:87], v[218:219], v[86:87]
	v_pk_fma_f32 v[86:87], v[234:235], v[86:87], v[250:251]
	v_pk_fma_f32 v[84:85], v[232:233], v[84:85], v[248:249]
	s_nop 0
	v_cvt_pk_bf16_f32 v84, v84, v85
	v_cvt_pk_bf16_f32 v85, v86, v87
	global_store_dwordx2 v[128:129], v[84:85], off offset:256 sc0 sc1
	v_mul_f32_e32 v80, v80, v190
	v_mul_f32_e32 v81, v81, v190
	v_mul_f32_e32 v82, v82, v190
	v_mul_f32_e32 v83, v83, v190
	v_pk_mul_f32 v[80:81], v[220:221], v[80:81]
	v_pk_mul_f32 v[82:83], v[222:223], v[82:83]
	v_pk_fma_f32 v[82:83], v[238:239], v[82:83], v[186:187]
	v_pk_fma_f32 v[80:81], v[236:237], v[80:81], v[184:185]
	s_nop 0
	v_cvt_pk_bf16_f32 v80, v80, v81
	v_cvt_pk_bf16_f32 v81, v82, v83
	global_store_dwordx2 v[128:129], v[80:81], off offset:288 sc0 sc1
	v_add_co_u32_e32 v128, vcc, 0x8000, v128
	s_nop 1
	v_addc_co_u32_e32 v129, vcc, 0, v129, vcc
	v_mul_f32_e32 v76, v76, v191
	v_mul_f32_e32 v77, v77, v191
	v_mul_f32_e32 v78, v78, v191
	v_mul_f32_e32 v79, v79, v191
	v_pk_mul_f32 v[76:77], v[208:209], v[76:77]
	v_pk_mul_f32 v[78:79], v[210:211], v[78:79]
	v_pk_fma_f32 v[78:79], v[226:227], v[78:79], v[242:243]
	v_pk_fma_f32 v[76:77], v[224:225], v[76:77], v[240:241]
	s_nop 0
	v_cvt_pk_bf16_f32 v76, v76, v77
	v_cvt_pk_bf16_f32 v77, v78, v79
	global_store_dwordx2 v[128:129], v[76:77], off sc0 sc1
	v_mul_f32_e32 v72, v72, v191
	v_mul_f32_e32 v73, v73, v191
	v_mul_f32_e32 v74, v74, v191
	v_mul_f32_e32 v75, v75, v191
	v_pk_mul_f32 v[72:73], v[212:213], v[72:73]
	v_pk_mul_f32 v[74:75], v[214:215], v[74:75]
	v_pk_fma_f32 v[74:75], v[230:231], v[74:75], v[246:247]
	v_pk_fma_f32 v[72:73], v[228:229], v[72:73], v[244:245]
	s_nop 0
	v_cvt_pk_bf16_f32 v72, v72, v73
	v_cvt_pk_bf16_f32 v73, v74, v75
	global_store_dwordx2 v[128:129], v[72:73], off offset:32 sc0 sc1
	v_mul_f32_e32 v68, v68, v191
	v_mul_f32_e32 v69, v69, v191
	v_mul_f32_e32 v70, v70, v191
	v_mul_f32_e32 v71, v71, v191
	v_pk_mul_f32 v[68:69], v[216:217], v[68:69]
	v_pk_mul_f32 v[70:71], v[218:219], v[70:71]
	v_pk_fma_f32 v[70:71], v[234:235], v[70:71], v[250:251]
	v_pk_fma_f32 v[68:69], v[232:233], v[68:69], v[248:249]
	s_nop 0
	v_cvt_pk_bf16_f32 v68, v68, v69
	v_cvt_pk_bf16_f32 v69, v70, v71
	global_store_dwordx2 v[128:129], v[68:69], off offset:256 sc0 sc1
	v_mul_f32_e32 v64, v64, v191
	v_mul_f32_e32 v65, v65, v191
	v_mul_f32_e32 v66, v66, v191
	v_mul_f32_e32 v67, v67, v191
	v_pk_mul_f32 v[64:65], v[220:221], v[64:65]
	v_pk_mul_f32 v[66:67], v[222:223], v[66:67]
	v_pk_fma_f32 v[66:67], v[238:239], v[66:67], v[186:187]
	v_pk_fma_f32 v[64:65], v[236:237], v[64:65], v[184:185]
	s_nop 0
	v_cvt_pk_bf16_f32 v64, v64, v65
	v_cvt_pk_bf16_f32 v65, v66, v67
	global_store_dwordx2 v[128:129], v[64:65], off offset:288 sc0 sc1
	v_add_co_u32_e32 v128, vcc, 0x28000, v128
	s_nop 1
	v_addc_co_u32_e32 v129, vcc, 0, v129, vcc
	v_mul_f32_e32 v60, v60, v192
	v_mul_f32_e32 v61, v61, v192
	v_mul_f32_e32 v62, v62, v192
	v_mul_f32_e32 v63, v63, v192
	v_pk_mul_f32 v[60:61], v[208:209], v[60:61]
	v_pk_mul_f32 v[62:63], v[210:211], v[62:63]
	v_pk_fma_f32 v[62:63], v[226:227], v[62:63], v[242:243]
	v_pk_fma_f32 v[60:61], v[224:225], v[60:61], v[240:241]
	s_nop 0
	v_cvt_pk_bf16_f32 v60, v60, v61
	v_cvt_pk_bf16_f32 v61, v62, v63
	global_store_dwordx2 v[128:129], v[60:61], off sc0 sc1
	v_mul_f32_e32 v56, v56, v192
	v_mul_f32_e32 v57, v57, v192
	v_mul_f32_e32 v58, v58, v192
	v_mul_f32_e32 v59, v59, v192
	v_pk_mul_f32 v[56:57], v[212:213], v[56:57]
	v_pk_mul_f32 v[58:59], v[214:215], v[58:59]
	v_pk_fma_f32 v[58:59], v[230:231], v[58:59], v[246:247]
	v_pk_fma_f32 v[56:57], v[228:229], v[56:57], v[244:245]
	s_nop 0
	v_cvt_pk_bf16_f32 v56, v56, v57
	v_cvt_pk_bf16_f32 v57, v58, v59
	global_store_dwordx2 v[128:129], v[56:57], off offset:32 sc0 sc1
	v_mul_f32_e32 v52, v52, v192
	v_mul_f32_e32 v53, v53, v192
	v_mul_f32_e32 v54, v54, v192
	v_mul_f32_e32 v55, v55, v192
	v_pk_mul_f32 v[52:53], v[216:217], v[52:53]
	v_pk_mul_f32 v[54:55], v[218:219], v[54:55]
	v_pk_fma_f32 v[54:55], v[234:235], v[54:55], v[250:251]
	v_pk_fma_f32 v[52:53], v[232:233], v[52:53], v[248:249]
	s_nop 0
	v_cvt_pk_bf16_f32 v52, v52, v53
	v_cvt_pk_bf16_f32 v53, v54, v55
	global_store_dwordx2 v[128:129], v[52:53], off offset:256 sc0 sc1
	v_mul_f32_e32 v48, v48, v192
	v_mul_f32_e32 v49, v49, v192
	v_mul_f32_e32 v50, v50, v192
	v_mul_f32_e32 v51, v51, v192
	v_pk_mul_f32 v[48:49], v[220:221], v[48:49]
	v_pk_mul_f32 v[50:51], v[222:223], v[50:51]
	v_pk_fma_f32 v[50:51], v[238:239], v[50:51], v[186:187]
	v_pk_fma_f32 v[48:49], v[236:237], v[48:49], v[184:185]
	s_nop 0
	v_cvt_pk_bf16_f32 v48, v48, v49
	v_cvt_pk_bf16_f32 v49, v50, v51
	global_store_dwordx2 v[128:129], v[48:49], off offset:288 sc0 sc1
	v_add_co_u32_e32 v128, vcc, 0x8000, v128
	s_nop 1
	v_addc_co_u32_e32 v129, vcc, 0, v129, vcc
	v_mul_f32_e32 v44, v44, v193
	v_mul_f32_e32 v45, v45, v193
	v_mul_f32_e32 v46, v46, v193
	v_mul_f32_e32 v47, v47, v193
	v_pk_mul_f32 v[44:45], v[208:209], v[44:45]
	v_pk_mul_f32 v[46:47], v[210:211], v[46:47]
	v_pk_fma_f32 v[46:47], v[226:227], v[46:47], v[242:243]
	v_pk_fma_f32 v[44:45], v[224:225], v[44:45], v[240:241]
	s_nop 0
	v_cvt_pk_bf16_f32 v44, v44, v45
	v_cvt_pk_bf16_f32 v45, v46, v47
; __device__ __forceinline__ unsigned cvt_pk_bf16(float lo, float hi) { const f32x2_t v = {lo, hi}; const bf16x2_t b = __builtin_convertvector(v, bf16x2_t); return __builtin_bit_cast(unsigned, b); }
; template <bool FINAL>
; __device__ __forceinline__ void norm_rows(const float* xp, const float* xs, const float* X, const float* g, const float* sh, const float* sc, bf16_t* XN, float* out, int gw, int NGW, int lane, const float* part, int nsplit) {
;     ...
;         for (int j = 0; j < 4; ++j) { const int col = 4 * lane + 256 * j; const f32x4 gg = *(const f32x4*)(g + col);
;             if (FINAL) { *(f32x4*)(out + (size_t)row * D + col) = v[j] * rstd * gg; }
;             else { const f32x4 s1 = *(const f32x4*)(sc + (size_t)mr * 6144 + col), s0 = *(const f32x4*)(sh + (size_t)mr * 6144 + col);
;                 const f32x4 h = v[j] * rstd * gg * (s1 + 1.0f) + s0;
;                 *(u32x2*)(XN + (size_t)row * D + col) = (u32x2){cvt_pk_bf16(h[0], h[1]), cvt_pk_bf16(h[2], h[3])}; } }
	global_store_dwordx2 v[128:129], v[44:45], off sc0 sc1
	v_mul_f32_e32 v40, v40, v193
	v_mul_f32_e32 v41, v41, v193
	v_mul_f32_e32 v42, v42, v193
	v_mul_f32_e32 v43, v43, v193
	v_pk_mul_f32 v[40:41], v[212:213], v[40:41]
	v_pk_mul_f32 v[42:43], v[214:215], v[42:43]
	v_pk_fma_f32 v[42:43], v[230:231], v[42:43], v[246:247]
	v_pk_fma_f32 v[40:41], v[228:229], v[40:41], v[244:245]
	s_nop 0
	v_cvt_pk_bf16_f32 v40, v40, v41
	v_cvt_pk_bf16_f32 v41, v42, v43
	global_store_dwordx2 v[128:129], v[40:41], off offset:32 sc0 sc1
	v_mul_f32_e32 v36, v36, v193
	v_mul_f32_e32 v37, v37, v193
	v_mul_f32_e32 v38, v38, v193
	v_mul_f32_e32 v39, v39, v193
	v_pk_mul_f32 v[36:37], v[216:217], v[36:37]
	v_pk_mul_f32 v[38:39], v[218:219], v[38:39]
	v_pk_fma_f32 v[38:39], v[234:235], v[38:39], v[250:251]
	v_pk_fma_f32 v[36:37], v[232:233], v[36:37], v[248:249]
	s_nop 0
	v_cvt_pk_bf16_f32 v36, v36, v37
	v_cvt_pk_bf16_f32 v37, v38, v39
	global_store_dwordx2 v[128:129], v[36:37], off offset:256 sc0 sc1
	v_mul_f32_e32 v32, v32, v193
	v_mul_f32_e32 v33, v33, v193
	v_mul_f32_e32 v34, v34, v193
	v_mul_f32_e32 v35, v35, v193
	v_pk_mul_f32 v[32:33], v[220:221], v[32:33]
	v_pk_mul_f32 v[34:35], v[222:223], v[34:35]
	v_pk_fma_f32 v[34:35], v[238:239], v[34:35], v[186:187]
	v_pk_fma_f32 v[32:33], v[236:237], v[32:33], v[184:185]
	s_nop 0
	v_cvt_pk_bf16_f32 v32, v32, v33
	v_cvt_pk_bf16_f32 v33, v34, v35
	global_store_dwordx2 v[128:129], v[32:33], off offset:288 sc0 sc1
	v_add_co_u32_e32 v128, vcc, 0x8000, v128
	s_nop 1
	v_addc_co_u32_e32 v129, vcc, 0, v129, vcc
	v_mul_f32_e32 v28, v28, v194
	v_mul_f32_e32 v29, v29, v194
	v_mul_f32_e32 v30, v30, v194
	v_mul_f32_e32 v31, v31, v194
	v_pk_mul_f32 v[28:29], v[208:209], v[28:29]
	v_pk_mul_f32 v[30:31], v[210:211], v[30:31]
	v_pk_fma_f32 v[30:31], v[226:227], v[30:31], v[242:243]
	v_pk_fma_f32 v[28:29], v[224:225], v[28:29], v[240:241]
	s_nop 0
	v_cvt_pk_bf16_f32 v28, v28, v29
	v_cvt_pk_bf16_f32 v29, v30, v31
	global_store_dwordx2 v[128:129], v[28:29], off sc0 sc1
	v_mul_f32_e32 v24, v24, v194
	v_mul_f32_e32 v25, v25, v194
	v_mul_f32_e32 v26, v26, v194
	v_mul_f32_e32 v27, v27, v194
	v_pk_mul_f32 v[24:25], v[212:213], v[24:25]
	v_pk_mul_f32 v[26:27], v[214:215], v[26:27]
	v_pk_fma_f32 v[26:27], v[230:231], v[26:27], v[246:247]
	v_pk_fma_f32 v[24:25], v[228:229], v[24:25], v[244:245]
	s_nop 0
	v_cvt_pk_bf16_f32 v24, v24, v25
	v_cvt_pk_bf16_f32 v25, v26, v27
	global_store_dwordx2 v[128:129], v[24:25], off offset:32 sc0 sc1
	v_mul_f32_e32 v20, v20, v194
	v_mul_f32_e32 v21, v21, v194
	v_mul_f32_e32 v22, v22, v194
	v_mul_f32_e32 v23, v23, v194
	v_pk_mul_f32 v[20:21], v[216:217], v[20:21]
	v_pk_mul_f32 v[22:23], v[218:219], v[22:23]
	v_pk_fma_f32 v[22:23], v[234:235], v[22:23], v[250:251]
	v_pk_fma_f32 v[20:21], v[232:233], v[20:21], v[248:249]
	s_nop 0
	v_cvt_pk_bf16_f32 v20, v20, v21
	v_cvt_pk_bf16_f32 v21, v22, v23
	global_store_dwordx2 v[128:129], v[20:21], off offset:256 sc0 sc1
	v_mul_f32_e32 v16, v16, v194
	v_mul_f32_e32 v17, v17, v194
	v_mul_f32_e32 v18, v18, v194
	v_mul_f32_e32 v19, v19, v194
	v_pk_mul_f32 v[16:17], v[220:221], v[16:17]
	v_pk_mul_f32 v[18:19], v[222:223], v[18:19]
	v_pk_fma_f32 v[18:19], v[238:239], v[18:19], v[186:187]
	v_pk_fma_f32 v[16:17], v[236:237], v[16:17], v[184:185]
	s_nop 0
	v_cvt_pk_bf16_f32 v16, v16, v17
	v_cvt_pk_bf16_f32 v17, v18, v19
	global_store_dwordx2 v[128:129], v[16:17], off offset:288 sc0 sc1
	v_add_co_u32_e32 v128, vcc, 0x8000, v128
	s_nop 1
	v_addc_co_u32_e32 v129, vcc, 0, v129, vcc
	v_mul_f32_e32 v12, v12, v195
	v_mul_f32_e32 v13, v13, v195
	v_mul_f32_e32 v14, v14, v195
	v_mul_f32_e32 v15, v15, v195
	v_pk_mul_f32 v[12:13], v[208:209], v[12:13]
	v_pk_mul_f32 v[14:15], v[210:211], v[14:15]
	v_pk_fma_f32 v[14:15], v[226:227], v[14:15], v[242:243]
	v_pk_fma_f32 v[12:13], v[224:225], v[12:13], v[240:241]
	s_nop 0
	v_cvt_pk_bf16_f32 v12, v12, v13
	v_cvt_pk_bf16_f32 v13, v14, v15
	global_store_dwordx2 v[128:129], v[12:13], off sc0 sc1
	v_mul_f32_e32 v8, v8, v195
	v_mul_f32_e32 v9, v9, v195
	v_mul_f32_e32 v10, v10, v195
	v_mul_f32_e32 v11, v11, v195
	v_pk_mul_f32 v[8:9], v[212:213], v[8:9]
	v_pk_mul_f32 v[10:11], v[214:215], v[10:11]
	v_pk_fma_f32 v[10:11], v[230:231], v[10:11], v[246:247]
	v_pk_fma_f32 v[8:9], v[228:229], v[8:9], v[244:245]
	s_nop 0
	v_cvt_pk_bf16_f32 v8, v8, v9
	v_cvt_pk_bf16_f32 v9, v10, v11
	global_store_dwordx2 v[128:129], v[8:9], off offset:32 sc0 sc1
	v_mul_f32_e32 v4, v4, v195
	v_mul_f32_e32 v5, v5, v195
	v_mul_f32_e32 v6, v6, v195
	v_mul_f32_e32 v7, v7, v195
	v_pk_mul_f32 v[4:5], v[216:217], v[4:5]
	v_pk_mul_f32 v[6:7], v[218:219], v[6:7]
	v_pk_fma_f32 v[6:7], v[234:235], v[6:7], v[250:251]
	v_pk_fma_f32 v[4:5], v[232:233], v[4:5], v[248:249]
	s_nop 0
	v_cvt_pk_bf16_f32 v4, v4, v5
	v_cvt_pk_bf16_f32 v5, v6, v7
	global_store_dwordx2 v[128:129], v[4:5], off offset:256 sc0 sc1
	v_mul_f32_e32 v0, v0, v195
	v_mul_f32_e32 v1, v1, v195
	v_mul_f32_e32 v2, v2, v195
	v_mul_f32_e32 v3, v3, v195
	v_pk_mul_f32 v[0:1], v[220:221], v[0:1]
	v_pk_mul_f32 v[2:3], v[222:223], v[2:3]
	v_pk_fma_f32 v[2:3], v[238:239], v[2:3], v[186:187]
	v_pk_fma_f32 v[0:1], v[236:237], v[0:1], v[184:185]
	s_nop 0
	v_cvt_pk_bf16_f32 v0, v0, v1
	v_cvt_pk_bf16_f32 v1, v2, v3
	global_store_dwordx2 v[128:129], v[0:1], off offset:288 sc0 sc1
	s_waitcnt vmcnt(0)
	s_barrier
	s_cmp_eq_u32 s25, 0
	s_cbranch_scc0 .Lfz_out_noarr
	s_sub_u32 s2, s16, 0x7dff400
	s_subb_u32 s3, s17, 0
	s_lshl_b32 s74, s4, 2
	s_add_u32 s2, s2, s74
	s_addc_u32 s3, s3, 0
	s_mov_b64 exec, 1
	v_mov_b32_e32 v207, 0
	v_mov_b32_e32 v159, 1
	global_atomic_add v207, v159, s[2:3]
	s_mov_b64 exec, -1

; #define INP(i) ((const float*)ld_ptr(pb, (i)))
; #define PHASE_END if (ph + 1 < hi) grid_barrier((unsigned*)ws, (unsigned)G, tid, (volatile LAS unsigned*)(ldsl + XBST_OFF)); } ++ph;
; template <bool FINAL>
; __device__ __forceinline__ void norm_rows(const float* xp, const float* xs, const float* X, const float* g, const float* sh, const float* sc, bf16_t* XN, float* out, int gw, int NGW, int lane, const float* part, int nsplit) {
;     ...
;         if (nsplit > 0 && row >= MP) {
;             for (int sp = 0; sp < nsplit; ++sp) { const float* pr = part + ((size_t)sp * MS + (row - MP)) * D + 4 * lane;
; #pragma unroll
;                 for (int j = 0; j < 4; ++j) v[j] += *(const f32x4*)(pr + 256 * j); }
; #pragma unroll
;             for (int j = 0; j < 4; ++j) *(f32x4*)((float*)X + (size_t)row * D + 4 * lane + 256 * j) = v[j]; }
; __global__ void __launch_bounds__(512, 2) hybrid_fwd(Params P) {
;     ...
;         PHASE_BEGIN
;         norm_rows<false>(nullptr, nullptr, X, INP(10) + l * D, (MOD + (size_t)l * NMODROWS * 6144) + 3072, (MOD + (size_t)l * NMODROWS * 6144) + 4096, XN, nullptr, gw, NGW, lane, (const float*)(ws + WS_PART), D / 256);
;         PHASE_END
.LBB0_1707:
	s_andn2_b64 vcc, exec, s[0:1]
	s_cbranch_vccnz .LBB0_1769
	v_readlane_b32 s1, v253, 7
	v_readlane_b32 s0, v253, 0
	v_readlane_b32 s18, v253, 1
	v_readlane_b32 s12, v253, 2
	v_mov_b32_e32 v0, s1
	v_mbcnt_lo_u32_b32 v44, -1, 0
	v_mbcnt_hi_u32_b32 v44, -1, v44
	ds_read2_b64 v[0:3], v0 offset0:10 offset1:35
	s_lshl_b32 s0, s0, 3
	s_add_i32 s0, s0, s12
	s_add_i32 s0, s0, 0x3a00
	s_cmpk_lt_i32 s0, 0x4000
	s_cselect_b32 s0, 0x7fff, s0
	s_cmpk_gt_i32 s0, 0x41ff
	s_mov_b32 s13, 0x200000
	s_waitcnt lgkmcnt(0)
	v_readfirstlane_b32 s3, v3
	v_readfirstlane_b32 s2, v2
	v_readfirstlane_b32 s1, v1
	v_readfirstlane_b32 s5, v0
	s_mov_b32 s16, 0x600000
	s_cbranch_scc1 .LBB0_1715
	s_lshl_b32 s7, s96, 5
	s_add_i32 s7, s7, 32
	s_mov_b64 exec, 1
	v_mov_b32_e32 v100, 0x140
	s_mov_b32 s8, 0
.Lmy_n2w_poll:
	global_load_dword v101, v100, s[2:3] sc0 sc1
	s_waitcnt vmcnt(0)
	v_readfirstlane_b32 s9, v101
	s_cmp_ge_u32 s9, s7
	s_cbranch_scc1 .Lmy_n2w_ok
	s_add_i32 s8, s8, 1
	s_cmp_lt_u32 s8, 0x800
	s_cbranch_scc0 .Lmy_n2w_ok
	s_sleep 1
	s_branch .Lmy_n2w_poll

; #define PG8_STAGE(bufoff, gbase, voff) do { _Pragma("unroll") for (int _i = 0; _i < 2; ++_i) \
;         __builtin_amdgcn_global_load_lds((const unsigned*)((const char*)(gbase) + (voff)[_i]), (LAS unsigned*)(lds + (bufoff) + ldsw + _i * 8192), 16, 0, 0); } while (0)
; #define PG8_WAIT_V(n) asm volatile("s_waitcnt vmcnt(" #n ")" ::: "memory")
; #define PG8_BAR __builtin_amdgcn_s_barrier()
;     __device__ bool next(int i, Unit& u) const {
;         const long L = (long)i * G + c; if (c < 0 || L >= tot) return false;
;         if (nsplit > 0 && L >= nwg) { const int r = (int)L - nwg, su = r / nsplit, sp = r % nsplit; u.pm = nMfull + su / nN; u.pn = su % nN; u.z = 0; u.k0 = sp * 256; u.nt = 4; u.split = 1; return true; }
;         const int z = (int)(L / nwg); int wgid = (int)(L % nwg);
;         { const int q = nwg / NXCD, r = nwg % NXCD, xcd = wgid % NXCD, off = wgid / NXCD; wgid = (xcd < r ? xcd * (q + 1) : r * (q + 1) + (xcd - r) * q) + off; }
;         const int nig = WGM * nN, gid = wgid / nig, fm = gid * WGM, gsz = (nM - fm) < WGM ? (nM - fm) : WGM;
;         u.pm = fm + ((wgid % nig) % gsz); u.pn = (wgid % nig) / gsz; u.z = z; u.k0 = 0; u.nt = ntK; u.split = 0; return true;
; template <class Epi, bool ALIGN_EPI>
; __device__ __forceinline__ void gemm_phase(LAS unsigned char* lds, const Gemm g, const Order& S, const Epi& E, const int wave_id) {
;     ...
;     const char* cA = (const char*)g.A + (size_t)cur.z * g.sAz + (size_t)cur.pm * 2 * hstepA + (size_t)cur.k0 * 2; const char* cB = (const char*)g.Bt + (size_t)cur.z * g.sBz + (size_t)cur.pn * 2 * hstepB + (size_t)cur.k0 * 2;
;     PG8_STAGE(PG8_SB(0, 0), cB, voffB); PG8_STAGE(PG8_SB(0, 1), cB + hstepB, voffB); PG8_STAGE(PG8_SA(0, 0), cA, voffA); PG8_STAGE(PG8_SA(0, 1), cA + hstepA, voffA);
;     if (wr == 1) PG8_BAR;
;     PG8_WAIT_V(2); PG8_BAR;
;     PG8_STAGE(PG8_SB(1, 0), cB + kstep, voffB); PG8_STAGE(PG8_SA(1, 0), cA + kstep, voffA); PG8_STAGE(PG8_SB(1, 1), cB + hstepB + kstep, voffB);
;     PG8_WAIT_V(6); PG8_BAR;
.LBB0_1777:
	s_lshr_b32 s5, s26, 3
	s_add_u32 s27, s2, 0xc000000
	s_mul_i32 s74, s96, 0x580000
	s_addc_u32 s28, s3, 0
	s_lshl_b64 s[0:1], s[74:75], 1
	s_add_u32 s0, s2, s0
	s_addc_u32 s1, s3, s1
	s_add_u32 s29, s0, 0x3c00000
	s_addc_u32 s30, s1, 0
	s_lshl_b32 s31, s8, 10
	v_lshl_add_u32 v0, v8, 4, s31
	v_ashrrev_i32_e32 v1, 31, v0
	v_lshrrev_b32_e32 v1, 22, v1
	v_add_u32_e32 v1, v0, v1
	v_ashrrev_i32_e32 v9, 10, v1
	v_mul_i32_i24_e32 v1, 0x400, v9
	v_sub_u32_e32 v1, v0, v1
	v_lshrrev_b32_e32 v2, 4, v1
	v_bitop3_b32 v1, v2, v1, 32 bitop3:0x6c
	v_ashrrev_i32_e32 v3, 31, v1
	v_lshrrev_b32_e32 v3, 26, v3
	v_add_u32_e32 v3, v1, v3
	v_lshlrev_b32_e32 v2, 3, v9
	v_ashrrev_i32_e32 v10, 6, v3
	v_and_b32_e32 v3, 0xc0, v3
	v_and_b32_e32 v2, -16, v2
	v_sub_u32_e32 v1, v1, v3
	v_add_u32_e32 v2, v10, v2
	v_ashrrev_i16_sdwa v1, v201, sext(v1) dst_sel:DWORD dst_unused:UNUSED_PAD src0_sel:DWORD src1_sel:BYTE_0
	v_lshlrev_b32_e32 v4, 5, v9
	v_bfe_i32 v11, v1, 0, 16
	v_lshlrev_b32_e32 v1, 1, v2
	v_lshrrev_b32_e32 v3, 2, v2
	v_and_b32_e32 v5, 3, v10
	s_mov_b32 s0, 0x1fffe0
	v_and_b32_e32 v4, 32, v4
	v_and_b32_e32 v1, 24, v1
	v_and_b32_e32 v3, 4, v3
	v_and_or_b32 v5, v2, s0, v5
	v_or3_b32 v1, v5, v3, v1
	v_add_lshl_u32 v3, v4, v11, 1
	v_add_u32_e32 v0, 0x2000, v0
	v_lshl_add_u32 v160, v1, 11, v3
	v_ashrrev_i32_e32 v1, 31, v0
	v_lshrrev_b32_e32 v1, 22, v1
	v_add_u32_e32 v1, v0, v1
	v_ashrrev_i32_e32 v12, 10, v1
	v_mul_i32_i24_e32 v1, 0x400, v12
	v_sub_u32_e32 v0, v0, v1
	v_lshrrev_b32_e32 v1, 4, v0
	v_bitop3_b32 v0, v1, v0, 32 bitop3:0x6c
	v_lshl_add_u32 v128, v2, 11, v3
	v_ashrrev_i32_e32 v2, 31, v0
	v_lshrrev_b32_e32 v2, 26, v2
	v_lshlrev_b32_e32 v1, 3, v12
	v_add_u32_e32 v2, v0, v2
	v_and_b32_e32 v1, -16, v1
	v_ashrrev_i32_e32 v13, 6, v2
	v_add_u32_e32 v1, v13, v1
	v_and_b32_e32 v2, 0xffc0, v2
	v_and_b32_e32 v4, 3, v13
	v_sub_u32_e32 v0, v0, v2
	v_and_or_b32 v4, v1, s0, v4
	s_add_i32 s0, s4, s5
	v_lshrrev_b16_e32 v2, 7, v0
	s_and_b32 s1, s0, 0xffff
	v_and_b32_e32 v2, 1, v2
	s_mul_i32 s1, s1, 0xba2f
	v_add_u16_e32 v0, v0, v2
	s_lshr_b32 s1, s1, 23
	v_ashrrev_i16_sdwa v0, v201, sext(v0) dst_sel:DWORD dst_unused:UNUSED_PAD src0_sel:DWORD src1_sel:BYTE_0
	s_lshl_b32 s6, s1, 3
	v_bfe_i32 v14, v0, 0, 16
	v_lshlrev_b32_e32 v0, 1, v1
	v_lshrrev_b32_e32 v2, 2, v1
	s_sub_i32 s4, 0x42, s6
	s_mulk_i32 s1, 0xb0
	v_and_b32_e32 v0, 24, v0
	v_and_b32_e32 v2, 4, v2
	s_min_u32 s7, s4, 8
	s_sub_i32 s1, s0, s1
	v_or3_b32 v0, v4, v2, v0
	s_and_b32 s0, s1, 0xffff
	v_cvt_f32_ubyte0_e32 v4, s7
	v_cvt_f32_u32_e32 v2, s0
	v_rcp_iflag_f32_e32 v5, v4
	v_lshlrev_b32_e32 v3, 5, v12
	v_and_b32_e32 v3, 32, v3
	v_add_lshl_u32 v3, v3, v14, 1
	v_lshl_add_u32 v132, v0, 11, v3
	v_mul_f32_e32 v0, v2, v5
	v_trunc_f32_e32 v0, v0
	v_lshl_add_u32 v130, v1, 11, v3
	v_cvt_u32_f32_e32 v1, v0
	v_fma_f32 v0, -v0, v4, v2
	s_ashr_i32 s0, s8, 2
	v_cmp_ge_f32_e64 s[4:5], |v0|, v4
	v_readfirstlane_b32 s9, v1
	s_cmp_lg_u64 s[4:5], 0
	s_addc_u32 s4, s9, 0
	s_mul_i32 s5, s4, s7
	s_sub_i32 s1, s1, s5
	s_and_b32 s1, s1, 0xff
	s_add_i32 s44, s6, s1
	s_lshl_b32 s1, s44, 19
	s_add_u32 s18, s27, s1
	s_addc_u32 s19, s28, 0
	s_and_b32 s45, s4, 0xff
	s_lshl_b32 s1, s45, 19
	s_add_u32 s20, s29, s1
	s_addc_u32 s21, s30, 0
	s_add_i32 s34, s31, 0
	s_add_i32 m0, s34, 0x10000
	v_mov_b32_e32 v133, v161
	global_load_lds_dwordx4 v160, s[20:21]
	s_add_i32 m0, s34, 0x12000
	s_add_u32 s4, s20, 0x40000
	global_load_lds_dwordx4 v132, s[20:21]
	s_addc_u32 s5, s21, 0
	s_add_i32 m0, s34, 0x14000
	s_add_i32 s35, s34, 0x2000
	global_load_lds_dwordx4 v160, s[4:5]
	s_add_i32 m0, s34, 0x16000
	v_mov_b32_e32 v129, v161
	global_load_lds_dwordx4 v132, s[4:5]
	s_add_u32 s98, s2, 0xc00
	s_addc_u32 s99, s3, 0
	s_lshl_b32 s74, s44, 2
	s_add_u32 s98, s98, s74
	s_addc_u32 s99, s99, 0
	s_lshl_b32 s74, s96, 2
	s_add_i32 s74, s74, 4
	s_mov_b32 s72, 0
.Lmy_ge_poll:
	v_mov_b32_e32 v255, 0
	global_load_dword v255, v255, s[98:99] sc0 sc1
	s_waitcnt vmcnt(0)
	v_readfirstlane_b32 s32, v255
	s_cmp_ge_u32 s32, s74
	s_cbranch_scc1 .Lmy_ge_ok
	s_add_i32 s72, s72, 1
	s_cmp_lt_u32 s72, 0x800
	s_cbranch_scc0 .Lmy_ge_ok
	s_sleep 1
	s_branch .Lmy_ge_poll
.Lmy_ge_ok:
	s_mov_b32 m0, s34
	s_add_u32 s4, s18, 0x40000
	global_load_lds_dwordx4 v128, s[18:19]
	s_mov_b32 m0, s35
	s_addc_u32 s5, s19, 0
	s_add_i32 s36, s34, 0x4000
	global_load_lds_dwordx4 v130, s[18:19]
	s_mov_b32 m0, s36
	s_add_i32 s37, s34, 0x6000
	global_load_lds_dwordx4 v128, s[4:5]
	s_mov_b32 m0, s37
	v_mov_b32_e32 v131, v161
	global_load_lds_dwordx4 v130, s[4:5]
	s_cmp_eq_u32 s0, 1
	v_lshl_add_u64 v[6:7], s[20:21], 0, v[160:161]
	v_lshl_add_u64 v[4:5], s[20:21], 0, v[132:133]
	v_lshl_add_u64 v[0:1], s[18:19], 0, v[128:129]
	s_cselect_b64 s[4:5], -1, 0
	s_cmp_lg_u32 s0, 1
	v_lshl_add_u64 v[2:3], s[18:19], 0, v[130:131]
	s_cbranch_scc1 .LBB0_1779
	s_barrier

; template <class Epi, bool ALIGN_EPI>
; __device__ __forceinline__ void gemm_phase(LAS unsigned char* lds, const Gemm g, const Order& S, const Epi& E, const int wave_id) {
;     ...
;         const bool has_next = S.next(ui + 1, nxt);
;         const char* nA = has_next ? (const char*)g.A + (size_t)nxt.z * g.sAz + (size_t)nxt.pm * 2 * hstepA + (size_t)nxt.k0 * 2 : cA;
;         const char* nB = has_next ? (const char*)g.Bt + (size_t)nxt.z * g.sBz + (size_t)nxt.pn * 2 * hstepB + (size_t)nxt.k0 * 2 : cB;
.Lmy_gu_issue:
	s_cmp_eq_u64 s[0:1], 0
	s_cbranch_scc1 .Lmy_gu_cont
	s_lshl_b32 s74, s12, 2
	s_addk_i32 s74, 0xc00
	s_cmp_lt_i32 s12, 64
	s_cselect_b32 s74, s74, 0x148
	s_add_u32 s98, s27, 0xf4000000
	s_addc_u32 s99, s28, -1
	s_add_u32 s98, s98, s74
	s_addc_u32 s99, s99, 0
	v_mov_b32_e32 v255, 0
	global_load_dword v255, v255, s[98:99] sc0 sc1
	s_branch .Lmy_gu_cont
.Lmy_gu_check:
	s_cmp_eq_u64 s[0:1], 0
	s_cbranch_scc1 .Lmy_gu_cont
	s_lshl_b32 s74, s96, 2
	s_add_i32 s74, s74, 4
	s_lshl_b32 s32, s96, 10
	s_addk_i32 s32, 0x200
	s_cmp_lt_i32 s12, 64
	s_cselect_b32 s32, s74, s32
	v_readfirstlane_b32 s98, v255
	s_cmp_ge_u32 s98, s32
	s_cbranch_scc1 .Lmy_gu_cont
	s_mov_b32 s72, 0
.Lmy_gu_slow:
	s_waitcnt vmcnt(0)
	v_readfirstlane_b32 s98, v255
	s_cmp_ge_u32 s98, s32
	s_cbranch_scc1 .Lmy_gu_cont
	s_add_i32 s72, s72, 1
	s_cmp_lt_u32 s72, 0x800
	s_cbranch_scc0 .Lmy_gu_cont
	s_sleep 1
	s_lshl_b32 s74, s12, 2
	s_addk_i32 s74, 0xc00
	s_cmp_lt_i32 s12, 64
	s_cselect_b32 s74, s74, 0x148
	s_add_u32 s98, s27, 0xf4000000
	s_addc_u32 s99, s28, -1
	s_add_u32 s98, s98, s74
	s_addc_u32 s99, s99, 0
	v_mov_b32_e32 v255, 0
	global_load_dword v255, v255, s[98:99] sc0 sc1
	s_branch .Lmy_gu_slow
